# v36 + diff-attention finalize: RMSNorm reductions via DPP/permlane16_swap instead of ds_bpermute round trips; drop unit-end vmcnt(0)
# baseline (speedup 1.0000x reference)
; __device__ __forceinline__ void attn_diff_unit(LAS unsigned char* lds, const bf16_t* __restrict__ Q, const bf16_t* __restrict__ Kb, const bf16_t* __restrict__ VT, bf16_t* O,
;                                                int qrow0, int b, int h, int ntiles, float lam, const float* subln_g) {
;     ...
;     asm volatile("s_waitcnt vmcnt(0)" ::: "memory");
;     __syncthreads();
; __global__ void __launch_bounds__(512, 2) fwd_megakernel(Args a) {
;     ...
;               for (int u = blockIdx.x; u < nlat_u + nctx_u; u += G) {
.LBB0_1088:
	s_add_i32 s62, s62, s96
	s_cmp_ge_i32 s62, s61
	s_barrier
	s_cbranch_scc1 .LBB0_1139

; __device__ __forceinline__ void attn_diff_unit(LAS unsigned char* lds, const bf16_t* __restrict__ Q, const bf16_t* __restrict__ Kb, const bf16_t* __restrict__ VT, bf16_t* O,
;                                                int qrow0, int b, int h, int ntiles, float lam, const float* subln_g) {
;     ...
;     __syncthreads();
;     if (sub == 0) {
;         float ssq[16];
; #pragma unroll
;         for (int r = 0; r < 16; ++r) { float s = 0.f;
; #pragma unroll
;             for (int k = 0; k < 4; ++k) { const float d = o[k][r] - lam * ex[(wq * 64 + k * 16 + r) * 64 + lane]; o[k][r] = d; s += d * d; }
;             s += __shfl_xor(s, 1); s += __shfl_xor(s, 2); s += __shfl_xor(s, 4); s += __shfl_xor(s, 8); s += __shfl_xor(s, 16);
;             ssq[r] = rsqrtf(s * (1.f / 128.f) + EPS); }
.LBB0_1135:
	s_and_b64 vcc, exec, s[38:39]
	s_waitcnt lgkmcnt(0)
	s_barrier
	s_cbranch_vccnz .LBB0_1088
	s_lshl_b32 s2, s8, 8
	s_and_b32 s2, s2, 0xc000
	s_add_i32 s2, s2, 0
	v_cmp_lt_i32_e32 vcc, v226, v220
	v_lshl_add_u32 v118, v229, 2, s2
	ds_read2st64_b32 v[2:3], v118 offset1:1
	ds_read2st64_b32 v[4:5], v118 offset0:16 offset1:17
	v_cndmask_b32_e32 v0, v219, v226, vcc
	v_cmp_lt_i32_e32 vcc, v225, v220
	v_lshlrev_b32_e32 v113, 2, v0
	ds_read2st64_b32 v[8:9], v118 offset0:32 offset1:33
	ds_read2st64_b32 v[10:11], v118 offset0:48 offset1:49
	v_cndmask_b32_e32 v0, v219, v225, vcc
	v_cmp_lt_i32_e32 vcc, v224, v220
	v_lshlrev_b32_e32 v114, 2, v0
	s_waitcnt lgkmcnt(2)
	v_mov_b32_e32 v1, v4
	v_cndmask_b32_e32 v0, v219, v224, vcc
	v_cmp_lt_i32_e32 vcc, v223, v220
	v_lshlrev_b32_e32 v115, 2, v0
	v_mov_b32_e32 v4, v3
	v_cndmask_b32_e32 v0, v219, v223, vcc
	v_cmp_lt_i32_e32 vcc, v222, v220
	v_lshlrev_b32_e32 v116, 2, v0
	v_pk_fma_f32 v[26:27], v[204:205], v[4:5], v[98:99] neg_lo:[1,0,0] neg_hi:[1,0,0]
	v_cndmask_b32_e32 v0, v219, v222, vcc
	v_lshlrev_b32_e32 v117, 2, v0
	v_mov_b32_e32 v0, v2
	v_pk_fma_f32 v[24:25], v[204:205], v[0:1], v[96:97] neg_lo:[1,0,0] neg_hi:[1,0,0]
	s_waitcnt lgkmcnt(1)
	v_mov_b32_e32 v0, v8
	s_waitcnt lgkmcnt(0)
	v_mov_b32_e32 v1, v10
	v_mov_b32_e32 v10, v9
	v_pk_mul_f32 v[6:7], v[24:25], v[24:25]
	v_pk_fma_f32 v[0:1], v[204:205], v[0:1], v[94:95] neg_lo:[1,0,0] neg_hi:[1,0,0]
	v_pk_mul_f32 v[4:5], v[26:27], v[26:27]
	v_pk_fma_f32 v[2:3], v[204:205], v[10:11], v[48:49] neg_lo:[1,0,0] neg_hi:[1,0,0]
	v_pk_mul_f32 v[12:13], v[0:1], v[0:1]
	v_pk_mul_f32 v[8:9], v[2:3], v[2:3]
	v_mov_b32_e32 v10, v4
	v_mov_b32_e32 v11, v6
	v_mov_b32_e32 v6, v5
	v_pk_add_f32 v[4:5], v[10:11], v[6:7]
	v_mov_b32_e32 v6, v8
	v_mov_b32_e32 v7, v12
	v_pk_add_f32 v[4:5], v[4:5], v[6:7]
	v_mov_b32_e32 v12, v9
	v_pk_add_f32 v[4:5], v[4:5], v[12:13]
	s_nop 1
	v_add_f32_dpp v5, v5, v5 quad_perm:[1,0,3,2] row_mask:0xf bank_mask:0xf
	v_add_f32_dpp v4, v4, v4 quad_perm:[1,0,3,2] row_mask:0xf bank_mask:0xf
	s_nop 0
	s_mov_b32 s2, 0x358637bd
	v_mov_b64_e32 v[48:49], s[2:3]
	s_brev_b32 s2, 60
	v_readlane_b32 s4, v251, 24
	s_waitcnt lgkmcnt(0)
	v_add_f32_dpp v5, v5, v5 quad_perm:[2,3,0,1] row_mask:0xf bank_mask:0xf
	v_add_f32_dpp v4, v4, v4 quad_perm:[2,3,0,1] row_mask:0xf bank_mask:0xf
	s_nop 0
	v_readlane_b32 s8, v251, 28
	v_readlane_b32 s9, v251, 29
	v_lshlrev_b32_e32 v194, 1, v228
	v_readlane_b32 s18, v251, 38
	s_waitcnt lgkmcnt(0)
	v_add_f32_dpp v5, v5, v5 row_half_mirror row_mask:0xf bank_mask:0xf
	v_add_f32_dpp v4, v4, v4 row_half_mirror row_mask:0xf bank_mask:0xf
	s_nop 0
	v_readlane_b32 s19, v251, 39
	v_readlane_b32 s18, v252, 3
	v_readlane_b32 s19, v252, 4
	v_readlane_b32 s5, v251, 25
	s_waitcnt lgkmcnt(0)
	v_add_f32_dpp v5, v5, v5 row_mirror row_mask:0xf bank_mask:0xf
	v_add_f32_dpp v4, v4, v4 row_mirror row_mask:0xf bank_mask:0xf
	s_nop 0
	v_readlane_b32 s6, v251, 26
	v_readlane_b32 s7, v251, 27
	v_readlane_b32 s10, v251, 30
	v_readlane_b32 s11, v251, 31
	s_waitcnt lgkmcnt(0)
	v_mov_b32_e32 v7, v5
	v_mov_b32_e32 v6, v4
	s_nop 1
	v_permlane16_swap_b32_e32 v5, v7
	v_permlane16_swap_b32_e32 v4, v6
	v_readlane_b32 s12, v251, 32
	v_readlane_b32 s13, v251, 33
	v_readlane_b32 s14, v251, 34
	v_readlane_b32 s15, v251, 35
	s_waitcnt lgkmcnt(0)
	v_pk_add_f32 v[4:5], v[4:5], v[6:7]
	v_readlane_b32 s16, v251, 36
	v_pk_fma_f32 v[4:5], v[4:5], s[2:3], v[48:49] op_sel_hi:[1,0,0]
	v_readlane_b32 s17, v251, 37
	v_mul_f32_e32 v6, 0x4b800000, v5
	v_cmp_gt_f32_e64 s[38:39], s66, v5
	v_cmp_gt_f32_e32 vcc, s66, v4
	s_nop 0
	v_cndmask_b32_e64 v5, v5, v6, s[38:39]
	v_rsq_f32_e32 v5, v5
	s_nop 0
	v_mul_f32_e32 v6, 0x45800000, v5
	v_cndmask_b32_e64 v98, v5, v6, s[38:39]
	v_mul_f32_e32 v5, 0x4b800000, v4
	v_cndmask_b32_e32 v4, v4, v5, vcc
	v_rsq_f32_e32 v4, v4
	ds_read2st64_b32 v[6:7], v118 offset0:2 offset1:3
	ds_read2st64_b32 v[8:9], v118 offset0:18 offset1:19
	ds_read2st64_b32 v[12:13], v118 offset0:34 offset1:35
	ds_read2st64_b32 v[14:15], v118 offset0:50 offset1:51
	v_mul_f32_e32 v24, v24, v98
	v_mul_f32_e32 v5, 0x45800000, v4
	v_cndmask_b32_e32 v99, v4, v5, vcc
	s_waitcnt lgkmcnt(3)
	v_mov_b32_e32 v4, v6
	s_waitcnt lgkmcnt(2)
	v_mov_b32_e32 v5, v8
	v_mov_b32_e32 v8, v7
	v_pk_fma_f32 v[32:33], v[204:205], v[4:5], v[32:33] neg_lo:[1,0,0] neg_hi:[1,0,0]
	s_waitcnt lgkmcnt(1)
	v_mov_b32_e32 v4, v12
	s_waitcnt lgkmcnt(0)
	v_mov_b32_e32 v5, v14
	v_pk_fma_f32 v[34:35], v[204:205], v[8:9], v[92:93] neg_lo:[1,0,0] neg_hi:[1,0,0]
	v_mov_b32_e32 v14, v13
	v_pk_mul_f32 v[10:11], v[32:33], v[32:33]
	v_pk_fma_f32 v[4:5], v[204:205], v[4:5], v[88:89] neg_lo:[1,0,0] neg_hi:[1,0,0]
	v_pk_mul_f32 v[8:9], v[34:35], v[34:35]
	v_pk_fma_f32 v[6:7], v[204:205], v[14:15], v[90:91] neg_lo:[1,0,0] neg_hi:[1,0,0]
	v_pk_mul_f32 v[28:29], v[4:5], v[4:5]
	v_pk_mul_f32 v[12:13], v[6:7], v[6:7]
	v_mov_b32_e32 v14, v8
	v_mov_b32_e32 v15, v10
	v_mov_b32_e32 v10, v9
	v_pk_add_f32 v[8:9], v[14:15], v[10:11]
	v_mov_b32_e32 v10, v12
	v_mov_b32_e32 v11, v28
	v_pk_add_f32 v[8:9], v[8:9], v[10:11]
	v_mov_b32_e32 v28, v13
	v_pk_add_f32 v[8:9], v[8:9], v[28:29]
	s_nop 1
	v_add_f32_dpp v9, v9, v9 quad_perm:[1,0,3,2] row_mask:0xf bank_mask:0xf
	v_add_f32_dpp v8, v8, v8 quad_perm:[1,0,3,2] row_mask:0xf bank_mask:0xf
	s_nop 0
	v_mul_f32_e32 v25, v25, v98
	v_mul_f32_e32 v0, v0, v98
	v_mul_f32_e32 v1, v1, v98
	s_waitcnt lgkmcnt(0)
	v_add_f32_dpp v9, v9, v9 quad_perm:[2,3,0,1] row_mask:0xf bank_mask:0xf
	v_add_f32_dpp v8, v8, v8 quad_perm:[2,3,0,1] row_mask:0xf bank_mask:0xf
	s_nop 0
	s_waitcnt lgkmcnt(0)
	v_add_f32_dpp v9, v9, v9 row_half_mirror row_mask:0xf bank_mask:0xf
	v_add_f32_dpp v8, v8, v8 row_half_mirror row_mask:0xf bank_mask:0xf
	s_nop 0
	s_waitcnt lgkmcnt(0)
; __device__ __forceinline__ void attn_diff_unit(LAS unsigned char* lds, const bf16_t* __restrict__ Q, const bf16_t* __restrict__ Kb, const bf16_t* __restrict__ VT, bf16_t* O,
;                                                int qrow0, int b, int h, int ntiles, float lam, const float* subln_g) {
;     ...
;         for (int r = 0; r < 16; ++r) { float s = 0.f;
; #pragma unroll
;             for (int k = 0; k < 4; ++k) { const float d = o[k][r] - lam * ex[(wq * 64 + k * 16 + r) * 64 + lane]; o[k][r] = d; s += d * d; }
;             s += __shfl_xor(s, 1); s += __shfl_xor(s, 2); s += __shfl_xor(s, 4); s += __shfl_xor(s, 8); s += __shfl_xor(s, 16);
;             ssq[r] = rsqrtf(s * (1.f / 128.f) + EPS); }
	v_add_f32_dpp v9, v9, v9 row_mirror row_mask:0xf bank_mask:0xf
	v_add_f32_dpp v8, v8, v8 row_mirror row_mask:0xf bank_mask:0xf
	s_nop 0
	s_waitcnt lgkmcnt(0)
	v_mov_b32_e32 v11, v9
	v_mov_b32_e32 v10, v8
	s_nop 1
	v_permlane16_swap_b32_e32 v9, v11
	v_permlane16_swap_b32_e32 v8, v10
	s_waitcnt lgkmcnt(0)
	v_pk_add_f32 v[8:9], v[8:9], v[10:11]
	s_nop 0
	v_pk_fma_f32 v[8:9], v[8:9], s[2:3], v[48:49] op_sel_hi:[1,0,0]
	s_nop 0
	v_mul_f32_e32 v10, 0x4b800000, v9
	v_cmp_gt_f32_e64 s[38:39], s66, v9
	v_cmp_gt_f32_e32 vcc, s66, v8
	s_nop 0
	v_cndmask_b32_e64 v9, v9, v10, s[38:39]
	v_rsq_f32_e32 v9, v9
	s_nop 0
	v_mul_f32_e32 v10, 0x45800000, v9
	v_cndmask_b32_e64 v100, v9, v10, s[38:39]
	v_mul_f32_e32 v9, 0x4b800000, v8
	v_cndmask_b32_e32 v8, v8, v9, vcc
	v_rsq_f32_e32 v8, v8
	ds_read2st64_b32 v[10:11], v118 offset0:4 offset1:5
	ds_read2st64_b32 v[12:13], v118 offset0:20 offset1:21
	ds_read2st64_b32 v[28:29], v118 offset0:36 offset1:37
	ds_read2st64_b32 v[30:31], v118 offset0:52 offset1:53
	v_mul_f32_e32 v9, 0x45800000, v8
	v_cndmask_b32_e32 v101, v8, v9, vcc
	s_waitcnt lgkmcnt(3)
	v_mov_b32_e32 v8, v10
	s_waitcnt lgkmcnt(2)
	v_mov_b32_e32 v9, v12
	v_mov_b32_e32 v12, v11
	v_pk_fma_f32 v[36:37], v[204:205], v[8:9], v[82:83] neg_lo:[1,0,0] neg_hi:[1,0,0]
	s_waitcnt lgkmcnt(1)
	v_mov_b32_e32 v8, v28
	s_waitcnt lgkmcnt(0)
	v_mov_b32_e32 v9, v30
	v_pk_fma_f32 v[38:39], v[204:205], v[12:13], v[86:87] neg_lo:[1,0,0] neg_hi:[1,0,0]
	v_mov_b32_e32 v30, v29
	v_pk_mul_f32 v[14:15], v[36:37], v[36:37]
	v_pk_fma_f32 v[8:9], v[204:205], v[8:9], v[80:81] neg_lo:[1,0,0] neg_hi:[1,0,0]
	v_pk_mul_f32 v[12:13], v[38:39], v[38:39]
	v_pk_fma_f32 v[10:11], v[204:205], v[30:31], v[84:85] neg_lo:[1,0,0] neg_hi:[1,0,0]
	v_pk_mul_f32 v[44:45], v[8:9], v[8:9]
	v_pk_mul_f32 v[28:29], v[10:11], v[10:11]
	v_mov_b32_e32 v30, v12
	v_mov_b32_e32 v31, v14
	v_mov_b32_e32 v14, v13
	v_pk_add_f32 v[12:13], v[30:31], v[14:15]
	v_mov_b32_e32 v14, v28
	v_mov_b32_e32 v15, v44
	v_pk_add_f32 v[12:13], v[12:13], v[14:15]
	v_mov_b32_e32 v44, v29
	v_pk_add_f32 v[12:13], v[12:13], v[44:45]
	s_nop 1
	v_add_f32_dpp v13, v13, v13 quad_perm:[1,0,3,2] row_mask:0xf bank_mask:0xf
	v_add_f32_dpp v12, v12, v12 quad_perm:[1,0,3,2] row_mask:0xf bank_mask:0xf
	s_nop 0
	s_waitcnt lgkmcnt(0)
	v_add_f32_dpp v13, v13, v13 quad_perm:[2,3,0,1] row_mask:0xf bank_mask:0xf
	v_add_f32_dpp v12, v12, v12 quad_perm:[2,3,0,1] row_mask:0xf bank_mask:0xf
	s_nop 0
	s_waitcnt lgkmcnt(0)
	v_add_f32_dpp v13, v13, v13 row_half_mirror row_mask:0xf bank_mask:0xf
	v_add_f32_dpp v12, v12, v12 row_half_mirror row_mask:0xf bank_mask:0xf
	s_nop 0
	s_waitcnt lgkmcnt(0)
	v_add_f32_dpp v13, v13, v13 row_mirror row_mask:0xf bank_mask:0xf
	v_add_f32_dpp v12, v12, v12 row_mirror row_mask:0xf bank_mask:0xf
	s_nop 0
	s_waitcnt lgkmcnt(0)
	v_mov_b32_e32 v15, v13
	v_mov_b32_e32 v14, v12
	s_nop 1
	v_permlane16_swap_b32_e32 v13, v15
	v_permlane16_swap_b32_e32 v12, v14
	s_waitcnt lgkmcnt(0)
	v_pk_add_f32 v[12:13], v[12:13], v[14:15]
	s_nop 0
	v_pk_fma_f32 v[12:13], v[12:13], s[2:3], v[48:49] op_sel_hi:[1,0,0]
	s_nop 0
	v_mul_f32_e32 v14, 0x4b800000, v13
	v_cmp_gt_f32_e64 s[38:39], s66, v13
	v_cmp_gt_f32_e32 vcc, s66, v12
	s_nop 0
	v_cndmask_b32_e64 v13, v13, v14, s[38:39]
	v_rsq_f32_e32 v13, v13
	s_nop 0
	v_mul_f32_e32 v14, 0x45800000, v13
	v_cndmask_b32_e64 v102, v13, v14, s[38:39]
	v_mul_f32_e32 v13, 0x4b800000, v12
	v_cndmask_b32_e32 v12, v12, v13, vcc
	v_rsq_f32_e32 v12, v12
	ds_read2st64_b32 v[14:15], v118 offset0:6 offset1:7
	ds_read2st64_b32 v[30:31], v118 offset0:22 offset1:23
	ds_read2st64_b32 v[60:61], v118 offset0:38 offset1:39
	ds_read2st64_b32 v[62:63], v118 offset0:54 offset1:55
	v_mul_f32_e32 v13, 0x45800000, v12
	v_cndmask_b32_e32 v103, v12, v13, vcc
	s_waitcnt lgkmcnt(3)
	v_mov_b32_e32 v12, v14
	s_waitcnt lgkmcnt(2)
	v_mov_b32_e32 v13, v30
	v_pk_fma_f32 v[44:45], v[204:205], v[12:13], v[78:79] neg_lo:[1,0,0] neg_hi:[1,0,0]
	s_waitcnt lgkmcnt(1)
	v_mov_b32_e32 v12, v60
	s_waitcnt lgkmcnt(0)
	v_mov_b32_e32 v13, v62
	v_mov_b32_e32 v30, v15
	v_pk_fma_f32 v[12:13], v[204:205], v[12:13], v[72:73] neg_lo:[1,0,0] neg_hi:[1,0,0]
	v_pk_fma_f32 v[72:73], v[204:205], v[30:31], v[76:77] neg_lo:[1,0,0] neg_hi:[1,0,0]
	v_mov_b32_e32 v62, v61
	v_pk_mul_f32 v[28:29], v[44:45], v[44:45]
	v_pk_mul_f32 v[30:31], v[72:73], v[72:73]
	v_pk_fma_f32 v[14:15], v[204:205], v[62:63], v[74:75] neg_lo:[1,0,0] neg_hi:[1,0,0]
	v_pk_mul_f32 v[78:79], v[12:13], v[12:13]
	v_pk_mul_f32 v[60:61], v[14:15], v[14:15]
	v_mov_b32_e32 v62, v30
	v_mov_b32_e32 v63, v28
	v_mov_b32_e32 v28, v31
	v_pk_add_f32 v[28:29], v[62:63], v[28:29]
	v_mov_b32_e32 v30, v60
	v_mov_b32_e32 v31, v78
	v_pk_add_f32 v[28:29], v[28:29], v[30:31]
	v_mov_b32_e32 v78, v61
	v_pk_add_f32 v[28:29], v[28:29], v[78:79]
	s_nop 1
	v_add_f32_dpp v29, v29, v29 quad_perm:[1,0,3,2] row_mask:0xf bank_mask:0xf
	v_add_f32_dpp v28, v28, v28 quad_perm:[1,0,3,2] row_mask:0xf bank_mask:0xf
	s_nop 0
	s_waitcnt lgkmcnt(0)
	v_add_f32_dpp v29, v29, v29 quad_perm:[2,3,0,1] row_mask:0xf bank_mask:0xf
	v_add_f32_dpp v28, v28, v28 quad_perm:[2,3,0,1] row_mask:0xf bank_mask:0xf
	s_nop 0
	s_waitcnt lgkmcnt(0)
	v_add_f32_dpp v29, v29, v29 row_half_mirror row_mask:0xf bank_mask:0xf
	v_add_f32_dpp v28, v28, v28 row_half_mirror row_mask:0xf bank_mask:0xf
	s_nop 0
	s_waitcnt lgkmcnt(0)
	v_add_f32_dpp v29, v29, v29 row_mirror row_mask:0xf bank_mask:0xf
	v_add_f32_dpp v28, v28, v28 row_mirror row_mask:0xf bank_mask:0xf
	s_nop 0
	s_waitcnt lgkmcnt(0)
	v_mov_b32_e32 v31, v29
	v_mov_b32_e32 v30, v28
	s_nop 1
	v_permlane16_swap_b32_e32 v29, v31
	v_permlane16_swap_b32_e32 v28, v30
	s_waitcnt lgkmcnt(0)
; __device__ __forceinline__ void attn_diff_unit(LAS unsigned char* lds, const bf16_t* __restrict__ Q, const bf16_t* __restrict__ Kb, const bf16_t* __restrict__ VT, bf16_t* O,
;                                                int qrow0, int b, int h, int ntiles, float lam, const float* subln_g) {
;     ...
;         for (int r = 0; r < 16; ++r) { float s = 0.f;
; #pragma unroll
;             for (int k = 0; k < 4; ++k) { const float d = o[k][r] - lam * ex[(wq * 64 + k * 16 + r) * 64 + lane]; o[k][r] = d; s += d * d; }
;             s += __shfl_xor(s, 1); s += __shfl_xor(s, 2); s += __shfl_xor(s, 4); s += __shfl_xor(s, 8); s += __shfl_xor(s, 16);
;             ssq[r] = rsqrtf(s * (1.f / 128.f) + EPS); }
	v_pk_add_f32 v[28:29], v[28:29], v[30:31]
	s_nop 0
	v_pk_fma_f32 v[28:29], v[28:29], s[2:3], v[48:49] op_sel_hi:[1,0,0]
	s_nop 0
	v_mul_f32_e32 v30, 0x4b800000, v29
	v_cmp_gt_f32_e64 s[38:39], s66, v29
	v_cmp_gt_f32_e32 vcc, s66, v28
	s_nop 0
	v_cndmask_b32_e64 v29, v29, v30, s[38:39]
	v_rsq_f32_e32 v29, v29
	s_nop 0
	v_mul_f32_e32 v30, 0x45800000, v29
	v_cndmask_b32_e64 v104, v29, v30, s[38:39]
	v_mul_f32_e32 v29, 0x4b800000, v28
	v_cndmask_b32_e32 v28, v28, v29, vcc
	v_rsq_f32_e32 v28, v28
	s_nop 0
	v_mul_f32_e32 v29, 0x45800000, v28
	v_cndmask_b32_e32 v105, v28, v29, vcc
	ds_read2st64_b32 v[28:29], v118 offset0:8 offset1:9
	ds_read2st64_b32 v[30:31], v118 offset0:24 offset1:25
	s_waitcnt lgkmcnt(1)
	v_mov_b32_e32 v60, v28
	s_waitcnt lgkmcnt(0)
	v_mov_b32_e32 v61, v30
	v_pk_fma_f32 v[80:81], v[204:205], v[60:61], v[18:19] neg_lo:[1,0,0] neg_hi:[1,0,0]
	ds_read2st64_b32 v[18:19], v118 offset0:40 offset1:41
	ds_read2st64_b32 v[62:63], v118 offset0:56 offset1:57
	v_mov_b32_e32 v30, v29
	v_pk_fma_f32 v[82:83], v[204:205], v[30:31], v[70:71] neg_lo:[1,0,0] neg_hi:[1,0,0]
	v_pk_mul_f32 v[60:61], v[80:81], v[80:81]
	s_waitcnt lgkmcnt(1)
	v_mov_b32_e32 v74, v18
	s_waitcnt lgkmcnt(0)
	v_mov_b32_e32 v75, v62
	v_mov_b32_e32 v62, v19
	v_pk_fma_f32 v[16:17], v[204:205], v[74:75], v[16:17] neg_lo:[1,0,0] neg_hi:[1,0,0]
	v_pk_mul_f32 v[28:29], v[82:83], v[82:83]
	v_pk_fma_f32 v[18:19], v[204:205], v[62:63], v[68:69] neg_lo:[1,0,0] neg_hi:[1,0,0]
	v_pk_mul_f32 v[74:75], v[16:17], v[16:17]
	v_pk_mul_f32 v[30:31], v[18:19], v[18:19]
	v_mov_b32_e32 v62, v28
	v_mov_b32_e32 v63, v60
	v_mov_b32_e32 v60, v29
	v_pk_add_f32 v[28:29], v[62:63], v[60:61]
	v_mov_b32_e32 v60, v30
	v_mov_b32_e32 v61, v74
	v_pk_add_f32 v[28:29], v[28:29], v[60:61]
	v_mov_b32_e32 v74, v31
	v_pk_add_f32 v[28:29], v[28:29], v[74:75]
	s_nop 1
	v_add_f32_dpp v29, v29, v29 quad_perm:[1,0,3,2] row_mask:0xf bank_mask:0xf
	v_add_f32_dpp v28, v28, v28 quad_perm:[1,0,3,2] row_mask:0xf bank_mask:0xf
	s_nop 0
	s_waitcnt lgkmcnt(0)
	v_add_f32_dpp v29, v29, v29 quad_perm:[2,3,0,1] row_mask:0xf bank_mask:0xf
	v_add_f32_dpp v28, v28, v28 quad_perm:[2,3,0,1] row_mask:0xf bank_mask:0xf
	s_nop 0
	s_waitcnt lgkmcnt(0)
	v_add_f32_dpp v29, v29, v29 row_half_mirror row_mask:0xf bank_mask:0xf
	v_add_f32_dpp v28, v28, v28 row_half_mirror row_mask:0xf bank_mask:0xf
	s_nop 0
	s_waitcnt lgkmcnt(0)
	v_add_f32_dpp v29, v29, v29 row_mirror row_mask:0xf bank_mask:0xf
	v_add_f32_dpp v28, v28, v28 row_mirror row_mask:0xf bank_mask:0xf
	s_nop 0
	s_waitcnt lgkmcnt(0)
	v_mov_b32_e32 v31, v29
	v_mov_b32_e32 v30, v28
	s_nop 1
	v_permlane16_swap_b32_e32 v29, v31
	v_permlane16_swap_b32_e32 v28, v30
	s_waitcnt lgkmcnt(0)
	v_pk_add_f32 v[28:29], v[28:29], v[30:31]
	s_nop 0
	v_pk_fma_f32 v[28:29], v[28:29], s[2:3], v[48:49] op_sel_hi:[1,0,0]
	s_nop 0
	v_mul_f32_e32 v30, 0x4b800000, v29
	v_cmp_gt_f32_e64 s[38:39], s66, v29
	v_cmp_gt_f32_e32 vcc, s66, v28
	s_nop 0
	v_cndmask_b32_e64 v29, v29, v30, s[38:39]
	v_rsq_f32_e32 v29, v29
	s_nop 0
	v_mul_f32_e32 v30, 0x45800000, v29
	v_cndmask_b32_e64 v106, v29, v30, s[38:39]
	v_mul_f32_e32 v29, 0x4b800000, v28
	v_cndmask_b32_e32 v28, v28, v29, vcc
	v_rsq_f32_e32 v28, v28
	s_nop 0
	v_mul_f32_e32 v29, 0x45800000, v28
	v_cndmask_b32_e32 v107, v28, v29, vcc
	ds_read2st64_b32 v[28:29], v118 offset0:10 offset1:11
	ds_read2st64_b32 v[30:31], v118 offset0:26 offset1:27
	s_waitcnt lgkmcnt(1)
	v_mov_b32_e32 v60, v28
	s_waitcnt lgkmcnt(0)
	v_mov_b32_e32 v61, v30
	v_pk_fma_f32 v[84:85], v[204:205], v[60:61], v[22:23] neg_lo:[1,0,0] neg_hi:[1,0,0]
	ds_read2st64_b32 v[22:23], v118 offset0:42 offset1:43
	ds_read2st64_b32 v[62:63], v118 offset0:58 offset1:59
	v_mov_b32_e32 v30, v29
	v_pk_fma_f32 v[86:87], v[204:205], v[30:31], v[66:67] neg_lo:[1,0,0] neg_hi:[1,0,0]
	v_pk_mul_f32 v[60:61], v[84:85], v[84:85]
	s_waitcnt lgkmcnt(1)
	v_mov_b32_e32 v68, v22
	s_waitcnt lgkmcnt(0)
	v_mov_b32_e32 v69, v62
	v_mov_b32_e32 v62, v23
	v_pk_fma_f32 v[20:21], v[204:205], v[68:69], v[20:21] neg_lo:[1,0,0] neg_hi:[1,0,0]
	v_pk_mul_f32 v[28:29], v[86:87], v[86:87]
	v_pk_fma_f32 v[22:23], v[204:205], v[62:63], v[64:65] neg_lo:[1,0,0] neg_hi:[1,0,0]
	v_pk_mul_f32 v[68:69], v[20:21], v[20:21]
	v_pk_mul_f32 v[30:31], v[22:23], v[22:23]
	v_mov_b32_e32 v62, v28
	v_mov_b32_e32 v63, v60
	v_mov_b32_e32 v60, v29
	v_pk_add_f32 v[28:29], v[62:63], v[60:61]
	v_mov_b32_e32 v60, v30
	v_mov_b32_e32 v61, v68
	v_pk_add_f32 v[28:29], v[28:29], v[60:61]
	v_mov_b32_e32 v68, v31
	v_pk_add_f32 v[28:29], v[28:29], v[68:69]
	s_nop 1
	v_add_f32_dpp v29, v29, v29 quad_perm:[1,0,3,2] row_mask:0xf bank_mask:0xf
	v_add_f32_dpp v28, v28, v28 quad_perm:[1,0,3,2] row_mask:0xf bank_mask:0xf
	s_nop 0
	s_waitcnt lgkmcnt(0)
	v_add_f32_dpp v29, v29, v29 quad_perm:[2,3,0,1] row_mask:0xf bank_mask:0xf
	v_add_f32_dpp v28, v28, v28 quad_perm:[2,3,0,1] row_mask:0xf bank_mask:0xf
	s_nop 0
	s_waitcnt lgkmcnt(0)
	v_add_f32_dpp v29, v29, v29 row_half_mirror row_mask:0xf bank_mask:0xf
	v_add_f32_dpp v28, v28, v28 row_half_mirror row_mask:0xf bank_mask:0xf
	s_nop 0
	s_waitcnt lgkmcnt(0)
	v_add_f32_dpp v29, v29, v29 row_mirror row_mask:0xf bank_mask:0xf
	v_add_f32_dpp v28, v28, v28 row_mirror row_mask:0xf bank_mask:0xf
	s_nop 0
	s_waitcnt lgkmcnt(0)
	v_mov_b32_e32 v31, v29
	v_mov_b32_e32 v30, v28
	s_nop 1
	v_permlane16_swap_b32_e32 v29, v31
	v_permlane16_swap_b32_e32 v28, v30
	s_waitcnt lgkmcnt(0)
; __device__ __forceinline__ void attn_diff_unit(LAS unsigned char* lds, const bf16_t* __restrict__ Q, const bf16_t* __restrict__ Kb, const bf16_t* __restrict__ VT, bf16_t* O,
;                                                int qrow0, int b, int h, int ntiles, float lam, const float* subln_g) {
;     ...
;         for (int r = 0; r < 16; ++r) { float s = 0.f;
; #pragma unroll
;             for (int k = 0; k < 4; ++k) { const float d = o[k][r] - lam * ex[(wq * 64 + k * 16 + r) * 64 + lane]; o[k][r] = d; s += d * d; }
;             s += __shfl_xor(s, 1); s += __shfl_xor(s, 2); s += __shfl_xor(s, 4); s += __shfl_xor(s, 8); s += __shfl_xor(s, 16);
;             ssq[r] = rsqrtf(s * (1.f / 128.f) + EPS); }
	v_pk_add_f32 v[28:29], v[28:29], v[30:31]
	s_nop 0
	v_pk_fma_f32 v[28:29], v[28:29], s[2:3], v[48:49] op_sel_hi:[1,0,0]
	s_nop 0
	v_mul_f32_e32 v30, 0x4b800000, v29
	v_cmp_gt_f32_e64 s[38:39], s66, v29
	v_cmp_gt_f32_e32 vcc, s66, v28
	s_nop 0
	v_cndmask_b32_e64 v29, v29, v30, s[38:39]
	v_rsq_f32_e32 v29, v29
	s_nop 0
	v_mul_f32_e32 v30, 0x45800000, v29
	v_cndmask_b32_e64 v108, v29, v30, s[38:39]
	v_mul_f32_e32 v29, 0x4b800000, v28
	v_cndmask_b32_e32 v28, v28, v29, vcc
	v_rsq_f32_e32 v28, v28
	ds_read2st64_b32 v[30:31], v118 offset0:12 offset1:13
	ds_read2st64_b32 v[60:61], v118 offset0:28 offset1:29
	ds_read2st64_b32 v[62:63], v118 offset0:44 offset1:45
	ds_read2st64_b32 v[64:65], v118 offset0:60 offset1:61
	v_mul_f32_e32 v29, 0x45800000, v28
	v_cndmask_b32_e32 v109, v28, v29, vcc
	s_waitcnt lgkmcnt(3)
	v_mov_b32_e32 v28, v30
	s_waitcnt lgkmcnt(2)
	v_mov_b32_e32 v29, v60
	v_mov_b32_e32 v60, v31
	v_pk_fma_f32 v[88:89], v[204:205], v[28:29], v[54:55] neg_lo:[1,0,0] neg_hi:[1,0,0]
	s_waitcnt lgkmcnt(1)
	v_mov_b32_e32 v28, v62
	s_waitcnt lgkmcnt(0)
	v_mov_b32_e32 v29, v64
	v_pk_fma_f32 v[90:91], v[204:205], v[60:61], v[58:59] neg_lo:[1,0,0] neg_hi:[1,0,0]
	v_mov_b32_e32 v64, v63
	v_pk_mul_f32 v[54:55], v[88:89], v[88:89]
	v_pk_fma_f32 v[28:29], v[204:205], v[28:29], v[52:53] neg_lo:[1,0,0] neg_hi:[1,0,0]
	v_pk_mul_f32 v[58:59], v[90:91], v[90:91]
	v_pk_fma_f32 v[30:31], v[204:205], v[64:65], v[56:57] neg_lo:[1,0,0] neg_hi:[1,0,0]
	v_pk_mul_f32 v[52:53], v[28:29], v[28:29]
	v_pk_mul_f32 v[56:57], v[30:31], v[30:31]
	v_mov_b32_e32 v60, v58
	v_mov_b32_e32 v61, v54
	v_mov_b32_e32 v54, v59
	v_pk_add_f32 v[54:55], v[60:61], v[54:55]
	v_mov_b32_e32 v58, v56
	v_mov_b32_e32 v59, v52
	v_pk_add_f32 v[54:55], v[54:55], v[58:59]
	v_mov_b32_e32 v52, v57
	v_pk_add_f32 v[52:53], v[54:55], v[52:53]
	s_nop 1
	v_add_f32_dpp v53, v53, v53 quad_perm:[1,0,3,2] row_mask:0xf bank_mask:0xf
	v_add_f32_dpp v52, v52, v52 quad_perm:[1,0,3,2] row_mask:0xf bank_mask:0xf
	s_nop 0
	s_waitcnt lgkmcnt(0)
	v_add_f32_dpp v53, v53, v53 quad_perm:[2,3,0,1] row_mask:0xf bank_mask:0xf
	v_add_f32_dpp v52, v52, v52 quad_perm:[2,3,0,1] row_mask:0xf bank_mask:0xf
	s_nop 0
	s_waitcnt lgkmcnt(0)
	v_add_f32_dpp v53, v53, v53 row_half_mirror row_mask:0xf bank_mask:0xf
	v_add_f32_dpp v52, v52, v52 row_half_mirror row_mask:0xf bank_mask:0xf
	s_nop 0
	s_waitcnt lgkmcnt(0)
	v_add_f32_dpp v53, v53, v53 row_mirror row_mask:0xf bank_mask:0xf
	v_add_f32_dpp v52, v52, v52 row_mirror row_mask:0xf bank_mask:0xf
	s_nop 0
	s_waitcnt lgkmcnt(0)
	v_mov_b32_e32 v55, v53
	v_mov_b32_e32 v54, v52
	s_nop 1
	v_permlane16_swap_b32_e32 v53, v55
	v_permlane16_swap_b32_e32 v52, v54
	s_waitcnt lgkmcnt(0)
	v_pk_add_f32 v[52:53], v[52:53], v[54:55]
	s_nop 0
	v_pk_fma_f32 v[52:53], v[52:53], s[2:3], v[48:49] op_sel_hi:[1,0,0]
	s_nop 0
	v_mul_f32_e32 v54, 0x4b800000, v53
	v_cmp_gt_f32_e64 s[38:39], s66, v53
	v_cmp_gt_f32_e32 vcc, s66, v52
	s_nop 0
	v_cndmask_b32_e64 v53, v53, v54, s[38:39]
	v_rsq_f32_e32 v53, v53
	s_nop 0
	v_mul_f32_e32 v54, 0x45800000, v53
	v_cndmask_b32_e64 v110, v53, v54, s[38:39]
	v_mul_f32_e32 v53, 0x4b800000, v52
	v_cndmask_b32_e32 v52, v52, v53, vcc
	v_rsq_f32_e32 v52, v52
	s_nop 0
	v_mul_f32_e32 v53, 0x45800000, v52
	v_cndmask_b32_e32 v111, v52, v53, vcc
	ds_read2st64_b32 v[52:53], v118 offset0:14 offset1:15
	ds_read2st64_b32 v[54:55], v118 offset0:30 offset1:31
	s_waitcnt lgkmcnt(1)
	v_mov_b32_e32 v56, v52
	s_waitcnt lgkmcnt(0)
	v_mov_b32_e32 v57, v54
	v_pk_fma_f32 v[92:93], v[204:205], v[56:57], v[50:51] neg_lo:[1,0,0] neg_hi:[1,0,0]
	ds_read2st64_b32 v[56:57], v118 offset0:46 offset1:47
	ds_read2st64_b32 v[58:59], v118 offset0:62 offset1:63
	v_mov_b32_e32 v54, v53
	v_pk_fma_f32 v[94:95], v[204:205], v[54:55], v[42:43] neg_lo:[1,0,0] neg_hi:[1,0,0]
	v_pk_mul_f32 v[50:51], v[92:93], v[92:93]
	s_waitcnt lgkmcnt(1)
	v_mov_b32_e32 v60, v56
	s_waitcnt lgkmcnt(0)
	v_mov_b32_e32 v61, v58
	v_mov_b32_e32 v58, v57
	v_pk_fma_f32 v[40:41], v[204:205], v[60:61], v[40:41] neg_lo:[1,0,0] neg_hi:[1,0,0]
	v_pk_mul_f32 v[52:53], v[94:95], v[94:95]
	v_pk_fma_f32 v[42:43], v[204:205], v[58:59], v[46:47] neg_lo:[1,0,0] neg_hi:[1,0,0]
	v_pk_mul_f32 v[60:61], v[40:41], v[40:41]
	v_pk_mul_f32 v[46:47], v[42:43], v[42:43]
	v_mov_b32_e32 v54, v52
	v_mov_b32_e32 v55, v50
	v_mov_b32_e32 v50, v53
	v_pk_add_f32 v[50:51], v[54:55], v[50:51]
	v_mov_b32_e32 v52, v46
	v_mov_b32_e32 v53, v60
	v_pk_add_f32 v[50:51], v[50:51], v[52:53]
	v_mov_b32_e32 v60, v47
	v_pk_add_f32 v[46:47], v[50:51], v[60:61]
	s_nop 1
	v_add_f32_dpp v47, v47, v47 quad_perm:[1,0,3,2] row_mask:0xf bank_mask:0xf
	v_add_f32_dpp v46, v46, v46 quad_perm:[1,0,3,2] row_mask:0xf bank_mask:0xf
	s_nop 0
	s_waitcnt lgkmcnt(0)
	v_add_f32_dpp v47, v47, v47 quad_perm:[2,3,0,1] row_mask:0xf bank_mask:0xf
	v_add_f32_dpp v46, v46, v46 quad_perm:[2,3,0,1] row_mask:0xf bank_mask:0xf
	s_nop 0
	s_waitcnt lgkmcnt(0)
	v_add_f32_dpp v47, v47, v47 row_half_mirror row_mask:0xf bank_mask:0xf
	v_add_f32_dpp v46, v46, v46 row_half_mirror row_mask:0xf bank_mask:0xf
	s_nop 0
	s_waitcnt lgkmcnt(0)
	v_add_f32_dpp v47, v47, v47 row_mirror row_mask:0xf bank_mask:0xf
	v_add_f32_dpp v46, v46, v46 row_mirror row_mask:0xf bank_mask:0xf
	s_nop 0
	s_waitcnt lgkmcnt(0)
	v_mov_b32_e32 v51, v47
	v_mov_b32_e32 v50, v46
	s_nop 1
	v_permlane16_swap_b32_e32 v47, v51
	v_permlane16_swap_b32_e32 v46, v50
	s_waitcnt lgkmcnt(0)
; __device__ __forceinline__ unsigned short f2bf(float f) { unsigned u = __builtin_bit_cast(unsigned, f); return (unsigned short)((u + 0x7fffu + ((u >> 16) & 1u)) >> 16); }
; __device__ __forceinline__ int crow(int r, int hi) { return (r & 3) + 8 * (r >> 2) + 4 * hi; }
; __device__ __forceinline__ void attn_diff_unit(LAS unsigned char* lds, const bf16_t* __restrict__ Q, const bf16_t* __restrict__ Kb, const bf16_t* __restrict__ VT, bf16_t* O,
;                                                int qrow0, int b, int h, int ntiles, float lam, const float* subln_g) {
;     ...
;             ssq[r] = rsqrtf(s * (1.f / 128.f) + EPS); }
; #pragma unroll
;         for (int k = 0; k < 4; ++k) { const float g = subln_g[k * 32 + r32] * (1.f - LAM_INIT);
; #pragma unroll
;             for (int r = 0; r < 16; ++r) O[(size_t)(qrow0 + 32 * wq + crow(r, hi)) * D + h * 128 + k * 32 + r32] = f2bf(o[k][r] * ssq[r] * g); }
	v_pk_add_f32 v[46:47], v[46:47], v[50:51]
	s_nop 0
	v_pk_fma_f32 v[46:47], v[46:47], s[2:3], v[48:49] op_sel_hi:[1,0,0]
	s_lshl_b32 s2, s76, 7
	v_mul_f32_e32 v48, 0x4b800000, v47
	v_cmp_gt_f32_e64 s[38:39], s66, v47
	v_cmp_gt_f32_e32 vcc, s66, v46
	s_ashr_i32 s3, s2, 31
	v_cndmask_b32_e64 v47, v47, v48, s[38:39]
	v_rsq_f32_e32 v47, v47
	s_lshl_b64 s[2:3], s[2:3], 1
	s_add_u32 s2, s72, s2
	s_addc_u32 s3, s73, s3
	v_mul_f32_e32 v48, 0x45800000, v47
	v_cndmask_b32_e64 v113, v47, v48, s[38:39]
	v_mul_f32_e32 v47, 0x4b800000, v46
	v_cndmask_b32_e32 v46, v46, v47, vcc
	v_rsq_f32_e32 v46, v46
	v_lshl_add_u64 v[96:97], s[2:3], 0, v[194:195]
	v_mul_f32_e32 v47, 0x45800000, v46
	v_cndmask_b32_e32 v114, v46, v47, vcc
	v_or_b32_e32 v46, s77, v112
	v_lshlrev_b32_e32 v112, 2, v228
	v_add_u32_e32 v78, s63, v46
	global_load_dword v46, v112, s[8:9]
	v_ashrrev_i32_e32 v79, 31, v78
	v_add_u32_e32 v48, 1, v78
	v_ashrrev_i32_e32 v49, 31, v48
	v_lshlrev_b64 v[48:49], 11, v[48:49]
	v_lshl_add_u64 v[48:49], v[96:97], 0, v[48:49]
	v_add_u32_e32 v50, 2, v78
	v_ashrrev_i32_e32 v51, 31, v50
	v_lshlrev_b64 v[50:51], 11, v[50:51]
	v_lshl_add_u64 v[50:51], v[96:97], 0, v[50:51]
	v_add_u32_e32 v52, 3, v78
	v_ashrrev_i32_e32 v53, 31, v52
	v_lshlrev_b64 v[52:53], 11, v[52:53]
	v_lshl_add_u64 v[52:53], v[96:97], 0, v[52:53]
	v_add_u32_e32 v54, 8, v78
	v_ashrrev_i32_e32 v55, 31, v54
	v_lshlrev_b64 v[54:55], 11, v[54:55]
	v_lshl_add_u64 v[54:55], v[96:97], 0, v[54:55]
	v_add_u32_e32 v56, 9, v78
	v_ashrrev_i32_e32 v57, 31, v56
	v_lshlrev_b64 v[56:57], 11, v[56:57]
	v_lshl_add_u64 v[56:57], v[96:97], 0, v[56:57]
	v_add_u32_e32 v58, 10, v78
	v_ashrrev_i32_e32 v59, 31, v58
	v_lshlrev_b64 v[58:59], 11, v[58:59]
	v_lshl_add_u64 v[58:59], v[96:97], 0, v[58:59]
	v_add_u32_e32 v60, 11, v78
	v_ashrrev_i32_e32 v61, 31, v60
	v_lshlrev_b64 v[60:61], 11, v[60:61]
	v_lshl_add_u64 v[60:61], v[96:97], 0, v[60:61]
	v_add_u32_e32 v62, 16, v78
	v_ashrrev_i32_e32 v63, 31, v62
	v_lshlrev_b64 v[62:63], 11, v[62:63]
	v_lshl_add_u64 v[62:63], v[96:97], 0, v[62:63]
	v_add_u32_e32 v64, 17, v78
	v_ashrrev_i32_e32 v65, 31, v64
	v_lshlrev_b64 v[64:65], 11, v[64:65]
	v_lshl_add_u64 v[64:65], v[96:97], 0, v[64:65]
	v_add_u32_e32 v66, 18, v78
	v_ashrrev_i32_e32 v67, 31, v66
	v_lshlrev_b64 v[66:67], 11, v[66:67]
	v_lshl_add_u64 v[66:67], v[96:97], 0, v[66:67]
	v_add_u32_e32 v68, 19, v78
	v_ashrrev_i32_e32 v69, 31, v68
	v_lshlrev_b64 v[68:69], 11, v[68:69]
	v_lshl_add_u64 v[68:69], v[96:97], 0, v[68:69]
	v_add_u32_e32 v70, 24, v78
	v_ashrrev_i32_e32 v71, 31, v70
	v_lshlrev_b64 v[70:71], 11, v[70:71]
	v_lshl_add_u64 v[70:71], v[96:97], 0, v[70:71]
	v_add_u32_e32 v74, 25, v78
	v_ashrrev_i32_e32 v75, 31, v74
	v_lshlrev_b64 v[74:75], 11, v[74:75]
	v_lshl_add_u64 v[74:75], v[96:97], 0, v[74:75]
	v_add_u32_e32 v76, 26, v78
	v_ashrrev_i32_e32 v77, 31, v76
	v_lshlrev_b64 v[76:77], 11, v[76:77]
	v_lshl_add_u64 v[76:77], v[96:97], 0, v[76:77]
	s_waitcnt vmcnt(0)
	v_mul_f32_e32 v115, 0x3f24fd5c, v46
	v_mul_f32_e32 v24, v24, v115
	v_bfe_u32 v46, v24, 16, 1
	v_add3_u32 v24, v24, v46, s0
	v_lshlrev_b64 v[46:47], 11, v[78:79]
	v_lshl_add_u64 v[46:47], v[96:97], 0, v[46:47]
	global_store_short_d16_hi v[46:47], v24, off
	v_mul_f32_e32 v24, v26, v99
	v_mul_f32_e32 v24, v24, v115
	v_bfe_u32 v26, v24, 16, 1
	v_add3_u32 v24, v24, v26, s0
	global_store_short_d16_hi v[48:49], v24, off
	v_mul_f32_e32 v24, v32, v100
	v_mul_f32_e32 v24, v24, v115
	v_bfe_u32 v26, v24, 16, 1
	v_add3_u32 v24, v24, v26, s0
	global_store_short_d16_hi v[50:51], v24, off
	v_mul_f32_e32 v24, v34, v101
	v_mul_f32_e32 v24, v24, v115
	v_bfe_u32 v26, v24, 16, 1
	v_add3_u32 v24, v24, v26, s0
	global_store_short_d16_hi v[52:53], v24, off
	v_mul_f32_e32 v24, v36, v102
	v_mul_f32_e32 v24, v24, v115
	v_bfe_u32 v26, v24, 16, 1
	v_add3_u32 v24, v24, v26, s0
	global_store_short_d16_hi v[54:55], v24, off
	v_mul_f32_e32 v24, v38, v103
	v_mul_f32_e32 v24, v24, v115
	v_bfe_u32 v26, v24, 16, 1
	v_add3_u32 v24, v24, v26, s0
	global_store_short_d16_hi v[56:57], v24, off
	v_mul_f32_e32 v24, v44, v104
	v_mul_f32_e32 v24, v24, v115
	v_bfe_u32 v26, v24, 16, 1
	v_add3_u32 v24, v24, v26, s0
	global_store_short_d16_hi v[58:59], v24, off
	v_mul_f32_e32 v24, v72, v105
	v_mul_f32_e32 v24, v24, v115
	v_bfe_u32 v26, v24, 16, 1
	v_add3_u32 v24, v24, v26, s0
	global_store_short_d16_hi v[60:61], v24, off
	v_mul_f32_e32 v24, v80, v106
	v_mul_f32_e32 v24, v24, v115
	v_bfe_u32 v26, v24, 16, 1
	v_add3_u32 v24, v24, v26, s0
	global_store_short_d16_hi v[62:63], v24, off
	v_mul_f32_e32 v24, v82, v107
	v_mul_f32_e32 v24, v24, v115
	v_bfe_u32 v26, v24, 16, 1
	v_add3_u32 v24, v24, v26, s0
	global_store_short_d16_hi v[64:65], v24, off
	v_mul_f32_e32 v24, v84, v108
	v_mul_f32_e32 v24, v24, v115
	v_bfe_u32 v26, v24, 16, 1
	v_add3_u32 v24, v24, v26, s0
	global_store_short_d16_hi v[66:67], v24, off
	v_mul_f32_e32 v24, v86, v109
	v_mul_f32_e32 v24, v24, v115
	v_bfe_u32 v26, v24, 16, 1
	v_add3_u32 v24, v24, v26, s0
	global_store_short_d16_hi v[68:69], v24, off
	v_mul_f32_e32 v24, v88, v110
	v_mul_f32_e32 v24, v24, v115
	v_bfe_u32 v26, v24, 16, 1
	v_add3_u32 v24, v24, v26, s0
	global_store_short_d16_hi v[70:71], v24, off
	v_mul_f32_e32 v24, v90, v111
	v_mul_f32_e32 v24, v24, v115
	v_bfe_u32 v26, v24, 16, 1
	v_add3_u32 v24, v24, v26, s0
	global_store_short_d16_hi v[74:75], v24, off
	v_mul_f32_e32 v24, v92, v113
	v_mul_f32_e32 v24, v115, v24
	v_bfe_u32 v26, v24, 16, 1
	v_add3_u32 v24, v24, v26, s0
	global_store_short_d16_hi v[76:77], v24, off
	v_mul_f32_e32 v24, v94, v114
	v_add_u32_e32 v78, 27, v78
	v_mul_f32_e32 v24, v115, v24
	v_ashrrev_i32_e32 v79, 31, v78
	v_bfe_u32 v26, v24, 16, 1
	v_lshlrev_b64 v[78:79], 11, v[78:79]
	v_add3_u32 v24, v24, v26, s0
	v_lshl_add_u64 v[78:79], v[96:97], 0, v[78:79]
	global_store_short_d16_hi v[78:79], v24, off
	global_load_dword v24, v112, s[8:9] offset:128
	s_waitcnt vmcnt(0)
; __device__ __forceinline__ unsigned short f2bf(float f) { unsigned u = __builtin_bit_cast(unsigned, f); return (unsigned short)((u + 0x7fffu + ((u >> 16) & 1u)) >> 16); }
; __device__ __forceinline__ int crow(int r, int hi) { return (r & 3) + 8 * (r >> 2) + 4 * hi; }
; __device__ __forceinline__ void attn_diff_unit(LAS unsigned char* lds, const bf16_t* __restrict__ Q, const bf16_t* __restrict__ Kb, const bf16_t* __restrict__ VT, bf16_t* O,
;                                                int qrow0, int b, int h, int ntiles, float lam, const float* subln_g) {
;     ...
;         for (int k = 0; k < 4; ++k) { const float g = subln_g[k * 32 + r32] * (1.f - LAM_INIT);
; #pragma unroll
;             for (int r = 0; r < 16; ++r) O[(size_t)(qrow0 + 32 * wq + crow(r, hi)) * D + h * 128 + k * 32 + r32] = f2bf(o[k][r] * ssq[r] * g); }
	v_mul_f32_e32 v24, 0x3f24fd5c, v24
	v_mul_f32_e32 v25, v25, v24
	v_bfe_u32 v26, v25, 16, 1
	v_add3_u32 v25, v25, v26, s0
	global_store_short_d16_hi v[46:47], v25, off offset:64
	v_mul_f32_e32 v25, v27, v99
	v_mul_f32_e32 v25, v25, v24
	v_bfe_u32 v26, v25, 16, 1
	v_add3_u32 v25, v25, v26, s0
	global_store_short_d16_hi v[48:49], v25, off offset:64
	v_mul_f32_e32 v25, v33, v100
	v_mul_f32_e32 v25, v25, v24
	v_bfe_u32 v26, v25, 16, 1
	v_add3_u32 v25, v25, v26, s0
	global_store_short_d16_hi v[50:51], v25, off offset:64
	v_mul_f32_e32 v25, v35, v101
	v_mul_f32_e32 v25, v25, v24
	v_bfe_u32 v26, v25, 16, 1
	v_add3_u32 v25, v25, v26, s0
	global_store_short_d16_hi v[52:53], v25, off offset:64
	v_mul_f32_e32 v25, v37, v102
	v_mul_f32_e32 v25, v25, v24
	v_bfe_u32 v26, v25, 16, 1
	v_add3_u32 v25, v25, v26, s0
	global_store_short_d16_hi v[54:55], v25, off offset:64
	v_mul_f32_e32 v25, v39, v103
	v_mul_f32_e32 v25, v25, v24
	v_bfe_u32 v26, v25, 16, 1
	v_add3_u32 v25, v25, v26, s0
	global_store_short_d16_hi v[56:57], v25, off offset:64
	v_mul_f32_e32 v25, v45, v104
	v_mul_f32_e32 v25, v25, v24
	v_bfe_u32 v26, v25, 16, 1
	v_add3_u32 v25, v25, v26, s0
	global_store_short_d16_hi v[58:59], v25, off offset:64
	v_mul_f32_e32 v25, v73, v105
	v_mul_f32_e32 v25, v25, v24
	v_bfe_u32 v26, v25, 16, 1
	v_add3_u32 v25, v25, v26, s0
	global_store_short_d16_hi v[60:61], v25, off offset:64
	v_mul_f32_e32 v25, v81, v106
	v_mul_f32_e32 v25, v25, v24
	v_bfe_u32 v26, v25, 16, 1
	v_add3_u32 v25, v25, v26, s0
	global_store_short_d16_hi v[62:63], v25, off offset:64
	v_mul_f32_e32 v25, v83, v107
	v_mul_f32_e32 v25, v25, v24
	v_bfe_u32 v26, v25, 16, 1
	v_add3_u32 v25, v25, v26, s0
	global_store_short_d16_hi v[64:65], v25, off offset:64
	v_mul_f32_e32 v25, v85, v108
	v_mul_f32_e32 v25, v25, v24
	v_bfe_u32 v26, v25, 16, 1
	v_add3_u32 v25, v25, v26, s0
	global_store_short_d16_hi v[66:67], v25, off offset:64
	v_mul_f32_e32 v25, v87, v109
	v_mul_f32_e32 v25, v25, v24
	v_bfe_u32 v26, v25, 16, 1
	v_add3_u32 v25, v25, v26, s0
	global_store_short_d16_hi v[68:69], v25, off offset:64
	v_mul_f32_e32 v25, v89, v110
	v_mul_f32_e32 v25, v25, v24
	v_bfe_u32 v26, v25, 16, 1
	v_add3_u32 v25, v25, v26, s0
	global_store_short_d16_hi v[70:71], v25, off offset:64
	v_mul_f32_e32 v25, v91, v111
	v_mul_f32_e32 v25, v25, v24
	v_bfe_u32 v26, v25, 16, 1
	v_add3_u32 v25, v25, v26, s0
	global_store_short_d16_hi v[74:75], v25, off offset:64
	v_mul_f32_e32 v25, v93, v113
	v_mul_f32_e32 v25, v25, v24
	v_bfe_u32 v26, v25, 16, 1
	v_add3_u32 v25, v25, v26, s0
	global_store_short_d16_hi v[76:77], v25, off offset:64
	v_mul_f32_e32 v25, v95, v114
	v_mul_f32_e32 v24, v25, v24
	v_bfe_u32 v25, v24, 16, 1
	v_add3_u32 v24, v24, v25, s0
	global_store_short_d16_hi v[78:79], v24, off offset:64
	global_load_dword v24, v112, s[8:9] offset:256
	s_waitcnt vmcnt(0)
; __device__ __forceinline__ unsigned short f2bf(float f) { unsigned u = __builtin_bit_cast(unsigned, f); return (unsigned short)((u + 0x7fffu + ((u >> 16) & 1u)) >> 16); }
; __device__ __forceinline__ int crow(int r, int hi) { return (r & 3) + 8 * (r >> 2) + 4 * hi; }
; __device__ __forceinline__ void attn_diff_unit(LAS unsigned char* lds, const bf16_t* __restrict__ Q, const bf16_t* __restrict__ Kb, const bf16_t* __restrict__ VT, bf16_t* O,
;                                                int qrow0, int b, int h, int ntiles, float lam, const float* subln_g) {
;     ...
;         for (int k = 0; k < 4; ++k) { const float g = subln_g[k * 32 + r32] * (1.f - LAM_INIT);
; #pragma unroll
;             for (int r = 0; r < 16; ++r) O[(size_t)(qrow0 + 32 * wq + crow(r, hi)) * D + h * 128 + k * 32 + r32] = f2bf(o[k][r] * ssq[r] * g); }
	v_mul_f32_e32 v24, 0x3f24fd5c, v24
	v_mul_f32_e32 v0, v0, v24
	v_bfe_u32 v25, v0, 16, 1
	v_add3_u32 v0, v0, v25, s0
	global_store_short_d16_hi v[46:47], v0, off offset:128
	v_mul_f32_e32 v0, v2, v99
	v_mul_f32_e32 v0, v0, v24
	v_bfe_u32 v2, v0, 16, 1
	v_add3_u32 v0, v0, v2, s0
	global_store_short_d16_hi v[48:49], v0, off offset:128
	v_mul_f32_e32 v0, v4, v100
	v_mul_f32_e32 v0, v0, v24
	v_bfe_u32 v2, v0, 16, 1
	v_add3_u32 v0, v0, v2, s0
	global_store_short_d16_hi v[50:51], v0, off offset:128
	v_mul_f32_e32 v0, v6, v101
	v_mul_f32_e32 v0, v0, v24
	v_bfe_u32 v2, v0, 16, 1
	v_add3_u32 v0, v0, v2, s0
	global_store_short_d16_hi v[52:53], v0, off offset:128
	v_mul_f32_e32 v0, v8, v102
	v_mul_f32_e32 v0, v0, v24
	v_bfe_u32 v2, v0, 16, 1
	v_add3_u32 v0, v0, v2, s0
	global_store_short_d16_hi v[54:55], v0, off offset:128
	v_mul_f32_e32 v0, v10, v103
	v_mul_f32_e32 v0, v0, v24
	v_bfe_u32 v2, v0, 16, 1
	v_add3_u32 v0, v0, v2, s0
	global_store_short_d16_hi v[56:57], v0, off offset:128
	v_mul_f32_e32 v0, v12, v104
	v_mul_f32_e32 v0, v0, v24
	v_bfe_u32 v2, v0, 16, 1
	v_add3_u32 v0, v0, v2, s0
	global_store_short_d16_hi v[58:59], v0, off offset:128
	v_mul_f32_e32 v0, v14, v105
	v_mul_f32_e32 v0, v0, v24
	v_bfe_u32 v2, v0, 16, 1
	v_add3_u32 v0, v0, v2, s0
	global_store_short_d16_hi v[60:61], v0, off offset:128
	v_mul_f32_e32 v0, v16, v106
	v_mul_f32_e32 v0, v0, v24
	v_bfe_u32 v2, v0, 16, 1
	v_add3_u32 v0, v0, v2, s0
	global_store_short_d16_hi v[62:63], v0, off offset:128
	v_mul_f32_e32 v0, v18, v107
	v_mul_f32_e32 v0, v0, v24
	v_bfe_u32 v2, v0, 16, 1
	v_add3_u32 v0, v0, v2, s0
	global_store_short_d16_hi v[64:65], v0, off offset:128
	v_mul_f32_e32 v0, v20, v108
	v_mul_f32_e32 v0, v0, v24
	v_bfe_u32 v2, v0, 16, 1
	v_add3_u32 v0, v0, v2, s0
	global_store_short_d16_hi v[66:67], v0, off offset:128
	v_mul_f32_e32 v0, v22, v109
	v_mul_f32_e32 v0, v0, v24
	v_bfe_u32 v2, v0, 16, 1
	v_add3_u32 v0, v0, v2, s0
	global_store_short_d16_hi v[68:69], v0, off offset:128
	v_mul_f32_e32 v0, v28, v110
	v_mul_f32_e32 v0, v0, v24
	v_bfe_u32 v2, v0, 16, 1
	v_add3_u32 v0, v0, v2, s0
	global_store_short_d16_hi v[70:71], v0, off offset:128
	v_mul_f32_e32 v0, v30, v111
	v_mul_f32_e32 v0, v0, v24
	v_bfe_u32 v2, v0, 16, 1
	v_add3_u32 v0, v0, v2, s0
	global_store_short_d16_hi v[74:75], v0, off offset:128
	v_mul_f32_e32 v0, v40, v113
	v_mul_f32_e32 v0, v0, v24
	v_bfe_u32 v2, v0, 16, 1
	v_add3_u32 v0, v0, v2, s0
	global_store_short_d16_hi v[76:77], v0, off offset:128
	v_mul_f32_e32 v0, v42, v114
	v_mul_f32_e32 v0, v0, v24
	v_bfe_u32 v2, v0, 16, 1
	v_add3_u32 v0, v0, v2, s0
	global_store_short_d16_hi v[78:79], v0, off offset:128
	global_load_dword v0, v112, s[8:9] offset:384
	s_waitcnt vmcnt(0)
	v_mul_f32_e32 v0, 0x3f24fd5c, v0
	v_mul_f32_e32 v1, v1, v0
	v_bfe_u32 v2, v1, 16, 1
	v_add3_u32 v1, v1, v2, s0
	global_store_short_d16_hi v[46:47], v1, off offset:192
	v_mul_f32_e32 v1, v3, v99
	v_mul_f32_e32 v1, v1, v0
	v_bfe_u32 v2, v1, 16, 1
	v_add3_u32 v1, v1, v2, s0
	global_store_short_d16_hi v[48:49], v1, off offset:192
	v_mul_f32_e32 v1, v5, v100
	v_mul_f32_e32 v1, v1, v0
	v_bfe_u32 v2, v1, 16, 1
	v_add3_u32 v1, v1, v2, s0
	global_store_short_d16_hi v[50:51], v1, off offset:192
	v_mul_f32_e32 v1, v7, v101
	v_mul_f32_e32 v1, v1, v0
	v_bfe_u32 v2, v1, 16, 1
	v_add3_u32 v1, v1, v2, s0
	global_store_short_d16_hi v[52:53], v1, off offset:192
	v_mul_f32_e32 v1, v9, v102
	v_mul_f32_e32 v1, v1, v0
	v_bfe_u32 v2, v1, 16, 1
	v_add3_u32 v1, v1, v2, s0
	global_store_short_d16_hi v[54:55], v1, off offset:192
	v_mul_f32_e32 v1, v11, v103
	v_mul_f32_e32 v1, v1, v0
	v_bfe_u32 v2, v1, 16, 1
	v_add3_u32 v1, v1, v2, s0
	global_store_short_d16_hi v[56:57], v1, off offset:192
	v_mul_f32_e32 v1, v13, v104
	v_mul_f32_e32 v1, v1, v0
	v_bfe_u32 v2, v1, 16, 1
	v_add3_u32 v1, v1, v2, s0
	global_store_short_d16_hi v[58:59], v1, off offset:192
	v_mul_f32_e32 v1, v15, v105
	v_mul_f32_e32 v1, v1, v0
	v_bfe_u32 v2, v1, 16, 1
	v_add3_u32 v1, v1, v2, s0
	global_store_short_d16_hi v[60:61], v1, off offset:192
	v_mul_f32_e32 v1, v17, v106
	v_mul_f32_e32 v1, v1, v0
	v_bfe_u32 v2, v1, 16, 1
	v_add3_u32 v1, v1, v2, s0
	global_store_short_d16_hi v[62:63], v1, off offset:192
	v_mul_f32_e32 v1, v19, v107
	v_mul_f32_e32 v1, v1, v0
	v_bfe_u32 v2, v1, 16, 1
	v_add3_u32 v1, v1, v2, s0
	global_store_short_d16_hi v[64:65], v1, off offset:192
	v_mul_f32_e32 v1, v21, v108
	v_mul_f32_e32 v1, v1, v0
	v_bfe_u32 v2, v1, 16, 1
	v_add3_u32 v1, v1, v2, s0
	global_store_short_d16_hi v[66:67], v1, off offset:192
	v_mul_f32_e32 v1, v23, v109
	v_mul_f32_e32 v1, v1, v0
	v_bfe_u32 v2, v1, 16, 1
	v_add3_u32 v1, v1, v2, s0
	global_store_short_d16_hi v[68:69], v1, off offset:192
	v_mul_f32_e32 v1, v29, v110
	v_mul_f32_e32 v1, v1, v0
	v_bfe_u32 v2, v1, 16, 1
	v_add3_u32 v1, v1, v2, s0
	global_store_short_d16_hi v[70:71], v1, off offset:192
	v_mul_f32_e32 v1, v31, v111
	v_mul_f32_e32 v1, v1, v0
	v_bfe_u32 v2, v1, 16, 1
	v_add3_u32 v1, v1, v2, s0
	global_store_short_d16_hi v[74:75], v1, off offset:192
	v_mul_f32_e32 v1, v41, v113
	v_mul_f32_e32 v1, v1, v0
	v_bfe_u32 v2, v1, 16, 1
	v_add3_u32 v1, v1, v2, s0
	global_store_short_d16_hi v[76:77], v1, off offset:192
	v_mul_f32_e32 v1, v43, v114
	v_mul_f32_e32 v0, v1, v0
	v_bfe_u32 v1, v0, 16, 1
	v_add3_u32 v0, v0, v1, s0
	global_store_short_d16_hi v[78:79], v0, off offset:192
	s_branch .LBB0_1088
